# P1/P9 unit headers: tile-group division by 8 done with shift/mask instead of float-reciprocal integer division
# baseline (speedup 1.0000x reference)
.LBB0_224:
	s_add_i32 s37, s37, 1
	s_mul_i32 s11, s37, s9
	s_mul_hi_u32 s15, s37, s3
	s_add_i32 s15, s15, s11
	s_mul_i32 s11, s37, s3
	s_add_u32 s40, s11, s2
	s_addc_u32 s41, s15, s71
	v_cmp_gt_i64_e32 vcc, s[40:41], v[158:159]
	v_cmp_lt_i64_e64 s[44:45], s[40:41], v[156:157]
	s_cbranch_vccnz .LBB0_226
	s_ashr_i32 s10, s40, 31
	s_lshr_b32 s10, s10, 29
	s_add_i32 s10, s40, s10
	s_ashr_i32 s11, s10, 3
	s_and_b32 s10, s10, -8
	s_sub_i32 s10, s40, s10
	s_cmp_lt_i32 s10, 0
	s_movk_i32 s14, 0x161
	s_cselect_b32 s14, s14, 0x160
	s_mul_i32 s10, s14, s10
	s_add_i32 s10, s10, s11
	s_mul_hi_i32 s11, s10, 0x2e8ba2e9
	s_lshr_b32 s14, s11, 31
	s_ashr_i32 s11, s11, 5
	s_add_i32 s11, s11, s14
	s_lshl_b32 s14, s11, 3
	s_mulk_i32 s11, 0xb0
	s_sub_i32 s11, s10, s11
	s_lshr_b32 s10, s11, 3
	s_and_b32 s11, s11, 7
	s_add_i32 s14, s11, s14

.LBB0_674:
	s_add_i32 s37, s37, 1
	s_mul_i32 s11, s37, s9
	s_mul_hi_u32 s15, s37, s3
	s_add_i32 s15, s15, s11
	s_mul_i32 s11, s37, s3
	s_add_u32 s42, s11, s2
	s_addc_u32 s43, s15, s71
	v_cmp_gt_i64_e32 vcc, s[42:43], v[158:159]
	v_cmp_lt_i64_e64 s[40:41], s[42:43], v[156:157]
	s_cbranch_vccnz .LBB0_676
	s_ashr_i32 s10, s42, 31
	s_lshr_b32 s10, s10, 29
	s_add_i32 s10, s42, s10
	s_ashr_i32 s11, s10, 3
	s_and_b32 s10, s10, -8
	s_sub_i32 s10, s42, s10
	s_cmp_lt_i32 s10, 0
	s_movk_i32 s14, 0x161
	s_cselect_b32 s14, s14, 0x160
	s_mul_i32 s10, s14, s10
	s_add_i32 s10, s10, s11
	s_mul_hi_i32 s11, s10, 0x2e8ba2e9
	s_lshr_b32 s14, s11, 31
	s_ashr_i32 s11, s11, 5
	s_add_i32 s11, s11, s14
	s_lshl_b32 s14, s11, 3
	s_mulk_i32 s11, 0xb0
	s_sub_i32 s11, s10, s11
	s_lshr_b32 s10, s11, 3
	s_and_b32 s11, s11, 7
	s_add_i32 s14, s11, s14
